# final (layer-1 tail) rownorm row loop software-pipelined as well
# speedup vs baseline: 1.0034x; 1.0023x over previous
; DI float bflo(unsigned u) { return __uint_as_float(u << 16); }
; DI float bfhi(unsigned u) { return __uint_as_float(u & 0xffff0000u); }
; DI float wave_sum(float v) { v += __shfl_xor(v, 32); v += __shfl_xor(v, 16); v += __shfl_xor(v, 8); v += __shfl_xor(v, 4); v += __shfl_xor(v, 2); v += __shfl_xor(v, 1); return v; }
; DI void rownorm_phase(const Params& P, const float* xin, const bf16_t* yin, float* xout, bf16_t* hout, int lg, int gate_idx, const float* w_post,
;                       int lh, int scale_idx, int shift_idx, const float* w_pre, char* smem) {
;     ...
;   for (int row = blockIdx.x * 8 + w; row < S_; row += gridDim.x * 8) {
;     f32x4 xv[8];
; #pragma unroll
;     for (int j = 0; j < 8; ++j) xv[j] = __builtin_nontemporal_load((const f32x4*)(xin + (size_t)row * 2048 + (j * 64 + lane) * 4));
;     if (yin) {
;       f32x4 yv[8]; float ss = 0.f;
; #pragma unroll
;       for (int j = 0; j < 8; ++j) { const u32x2 yb = __builtin_nontemporal_load((const u32x2*)(yin + (size_t)row * 2048 + (j * 64 + lane) * 4)); yv[j] = (f32x4){bflo(yb.x), bfhi(yb.x), bflo(yb.y), bfhi(yb.y)};
;         ss += yv[j].x * yv[j].x + yv[j].y * yv[j].y + yv[j].z * yv[j].z + yv[j].w * yv[j].w; }
;       ss = wave_sum(ss); const float r = rsqrtf(ss * (1.f / 2048.f) + EPS);
; #pragma unroll
;       for (int j = 0; j < 8; ++j) { const f32x4 a = *(const f32x4*)(A1 + (j * 64 + lane) * 4); xv[j] += a * (yv[j] * r); }
;     }
;     if (yin || xout != xin) {
; #pragma unroll
;       for (int j = 0; j < 8; ++j) __builtin_nontemporal_store(xv[j], (f32x4*)(xout + (size_t)row * 2048 + (j * 64 + lane) * 4));
.LBB0_1155:
	s_or_b64 exec, exec, s[0:1]
	v_ashrrev_i32_e32 v0, 6, v2
	v_readlane_b32 s0, v254, 3
	s_waitcnt lgkmcnt(0)
	s_barrier
	v_add_u32_e32 v36, s0, v0
	s_movk_i32 s0, 0x4000
	v_cmp_gt_i32_e32 vcc, s0, v36
	s_and_saveexec_b64 s[0:1], vcc
	s_movk_i32 s4, 0x3fff
	s_cbranch_execz .LBB0_1158
	s_waitcnt vmcnt(0)
	v_and_b32_e32 v5, 64, v239
	v_xor_b32_e32 v3, 32, v239
	v_add_u32_e32 v5, 64, v5
	v_cmp_lt_i32_e32 vcc, v3, v5
	v_and_b32_e32 v0, 63, v2
	v_lshlrev_b32_e32 v2, 2, v0
	v_cndmask_b32_e32 v3, v239, v3, vcc
	v_lshlrev_b32_e32 v92, 2, v3
	v_xor_b32_e32 v3, 16, v239
	v_cmp_lt_i32_e32 vcc, v3, v5
	v_lshlrev_b32_e32 v91, 4, v0
	v_or_b32_e32 v4, 0x400, v2
	v_cndmask_b32_e32 v3, v239, v3, vcc
	v_lshlrev_b32_e32 v93, 2, v3
	v_xor_b32_e32 v3, 8, v239
	v_cmp_lt_i32_e32 vcc, v3, v5
	v_or_b32_e32 v6, 0x500, v2
	v_or_b32_e32 v8, 0x600, v2
	v_cndmask_b32_e32 v3, v239, v3, vcc
	v_lshlrev_b32_e32 v94, 2, v3
	v_xor_b32_e32 v3, 4, v239
	v_cmp_lt_i32_e32 vcc, v3, v5
	v_or_b32_e32 v10, 0x700, v2
	v_lshlrev_b32_e32 v0, 3, v0
	v_cndmask_b32_e32 v3, v239, v3, vcc
	v_lshlrev_b32_e32 v95, 2, v3
	v_xor_b32_e32 v3, 2, v239
	v_cmp_lt_i32_e32 vcc, v3, v5
	v_lshl_add_u64 v[38:39], s[46:47], 0, v[0:1]
	s_mov_b64 s[2:3], 0
	v_cndmask_b32_e32 v3, v239, v3, vcc
	v_lshlrev_b32_e32 v96, 2, v3
	v_xor_b32_e32 v3, 1, v239
	v_cmp_lt_i32_e32 vcc, v3, v5
	v_lshlrev_b32_e32 v0, 2, v2
	v_lshlrev_b32_e32 v40, 2, v4
	v_cndmask_b32_e32 v3, v239, v3, vcc
	v_lshlrev_b32_e32 v97, 2, v3
	v_lshlrev_b32_e32 v42, 2, v6
	v_lshlrev_b32_e32 v44, 2, v8
	v_lshlrev_b32_e32 v46, 2, v10
	v_mov_b32_e32 v41, v1
	v_mov_b32_e32 v43, v1
	v_mov_b32_e32 v45, v1
	v_mov_b32_e32 v47, v1
	v_ashrrev_i32_e32 v141, 31, v36
	v_mov_b32_e32 v140, v36
	v_lshlrev_b64 v[142:143], 13, v[140:141]
	v_lshl_add_u64 v[142:143], v[34:35], 0, v[142:143]
	v_lshlrev_b64 v[144:145], 12, v[140:141]
	v_lshl_add_u64 v[146:147], v[142:143], 0, v[0:1]
	v_lshl_add_u64 v[144:145], v[38:39], 0, v[144:145]
	global_load_dwordx4 v[160:163], v[146:147], off nt
	global_load_dwordx4 v[164:167], v[146:147], off offset:1024 nt
	global_load_dwordx4 v[168:171], v[146:147], off offset:2048 nt
	global_load_dwordx4 v[172:175], v[146:147], off offset:3072 nt
	v_lshl_add_u64 v[148:149], v[142:143], 0, v[40:41]
	global_load_dwordx4 v[176:179], v[148:149], off nt
	v_lshl_add_u64 v[148:149], v[142:143], 0, v[46:47]
	global_load_dwordx4 v[188:191], v[148:149], off nt
	v_lshl_add_u64 v[148:149], v[142:143], 0, v[42:43]
	global_load_dwordx4 v[180:183], v[148:149], off nt
	v_lshl_add_u64 v[148:149], v[142:143], 0, v[44:45]
	global_load_dwordx4 v[184:187], v[148:149], off nt
	global_load_dwordx2 v[124:125], v[144:145], off nt
	global_load_dwordx2 v[126:127], v[144:145], off offset:512 nt
	global_load_dwordx2 v[128:129], v[144:145], off offset:1024 nt
	global_load_dwordx2 v[130:131], v[144:145], off offset:1536 nt
	global_load_dwordx2 v[132:133], v[144:145], off offset:2048 nt
	global_load_dwordx2 v[134:135], v[144:145], off offset:2560 nt
	global_load_dwordx2 v[136:137], v[144:145], off offset:3072 nt
	global_load_dwordx2 v[138:139], v[144:145], off offset:3584 nt
.LBB0_1157:
	v_ashrrev_i32_e32 v37, 31, v36
	v_lshlrev_b64 v[2:3], 13, v[36:37]
	v_lshl_add_u64 v[2:3], v[34:35], 0, v[2:3]
	v_lshl_add_u64 v[54:55], v[2:3], 0, v[0:1]
	v_mov_b32_e32 v41, v1
	v_mov_b32_e32 v43, v1
	v_mov_b32_e32 v45, v1
	v_mov_b32_e32 v47, v1
	v_lshl_add_u64 v[56:57], v[2:3], 0, v[40:41]
	v_lshl_add_u64 v[50:51], v[2:3], 0, v[42:43]
	v_lshl_add_u64 v[48:49], v[2:3], 0, v[44:45]
	v_lshl_add_u64 v[52:53], v[2:3], 0, v[46:47]
	s_waitcnt vmcnt(0)
	v_mov_b64_e32 v[30:31], v[160:161]
	v_mov_b64_e32 v[32:33], v[162:163]
	v_mov_b64_e32 v[26:27], v[164:165]
	v_mov_b64_e32 v[28:29], v[166:167]
	v_mov_b64_e32 v[22:23], v[168:169]
	v_mov_b64_e32 v[24:25], v[170:171]
	v_mov_b64_e32 v[18:19], v[172:173]
	v_mov_b64_e32 v[20:21], v[174:175]
	v_mov_b64_e32 v[14:15], v[176:177]
	v_mov_b64_e32 v[16:17], v[178:179]
	v_mov_b64_e32 v[2:3], v[188:189]
	v_mov_b64_e32 v[4:5], v[190:191]
	v_mov_b64_e32 v[10:11], v[180:181]
	v_mov_b64_e32 v[12:13], v[182:183]
	v_mov_b64_e32 v[6:7], v[184:185]
	v_mov_b64_e32 v[8:9], v[186:187]
	v_mov_b64_e32 v[58:59], v[124:125]
	v_mov_b64_e32 v[106:107], v[126:127]
	v_mov_b64_e32 v[108:109], v[128:129]
	v_mov_b64_e32 v[110:111], v[130:131]
	v_mov_b64_e32 v[84:85], v[132:133]
	v_mov_b64_e32 v[62:63], v[134:135]
	v_mov_b64_e32 v[98:99], v[136:137]
	v_mov_b64_e32 v[88:89], v[138:139]
	v_add_u32_e32 v140, s79, v36
	v_cmp_gt_i32_e32 vcc, 0x4000, v140
	s_and_saveexec_b64 s[12:13], vcc
	s_cbranch_execz .Lrn_pf_skip3
	v_ashrrev_i32_e32 v141, 31, v140
	v_lshlrev_b64 v[142:143], 13, v[140:141]
	v_lshl_add_u64 v[142:143], v[34:35], 0, v[142:143]
	v_lshlrev_b64 v[144:145], 12, v[140:141]
	v_lshl_add_u64 v[146:147], v[142:143], 0, v[0:1]
	v_lshl_add_u64 v[144:145], v[38:39], 0, v[144:145]
	global_load_dwordx4 v[160:163], v[146:147], off nt
	global_load_dwordx4 v[164:167], v[146:147], off offset:1024 nt
	global_load_dwordx4 v[168:171], v[146:147], off offset:2048 nt
	global_load_dwordx4 v[172:175], v[146:147], off offset:3072 nt
	v_lshl_add_u64 v[148:149], v[142:143], 0, v[40:41]
	global_load_dwordx4 v[176:179], v[148:149], off nt
	v_lshl_add_u64 v[148:149], v[142:143], 0, v[46:47]
	global_load_dwordx4 v[188:191], v[148:149], off nt
	v_lshl_add_u64 v[148:149], v[142:143], 0, v[42:43]
	global_load_dwordx4 v[180:183], v[148:149], off nt
	v_lshl_add_u64 v[148:149], v[142:143], 0, v[44:45]
	global_load_dwordx4 v[184:187], v[148:149], off nt
	global_load_dwordx2 v[124:125], v[144:145], off nt
	global_load_dwordx2 v[126:127], v[144:145], off offset:512 nt
	global_load_dwordx2 v[128:129], v[144:145], off offset:1024 nt
	global_load_dwordx2 v[130:131], v[144:145], off offset:1536 nt
	global_load_dwordx2 v[132:133], v[144:145], off offset:2048 nt
	global_load_dwordx2 v[134:135], v[144:145], off offset:2560 nt
	global_load_dwordx2 v[136:137], v[144:145], off offset:3072 nt
	global_load_dwordx2 v[138:139], v[144:145], off offset:3584 nt
; DI float bflo(unsigned u) { return __uint_as_float(u << 16); }
; DI float bfhi(unsigned u) { return __uint_as_float(u & 0xffff0000u); }
; DI float wave_sum(float v) { v += __shfl_xor(v, 32); v += __shfl_xor(v, 16); v += __shfl_xor(v, 8); v += __shfl_xor(v, 4); v += __shfl_xor(v, 2); v += __shfl_xor(v, 1); return v; }
; DI void rownorm_phase(const Params& P, const float* xin, const bf16_t* yin, float* xout, bf16_t* hout, int lg, int gate_idx, const float* w_post,
;                       int lh, int scale_idx, int shift_idx, const float* w_pre, char* smem) {
;     ...
;       f32x4 yv[8]; float ss = 0.f;
; #pragma unroll
;       for (int j = 0; j < 8; ++j) { const u32x2 yb = __builtin_nontemporal_load((const u32x2*)(yin + (size_t)row * 2048 + (j * 64 + lane) * 4)); yv[j] = (f32x4){bflo(yb.x), bfhi(yb.x), bflo(yb.y), bfhi(yb.y)};
;         ss += yv[j].x * yv[j].x + yv[j].y * yv[j].y + yv[j].z * yv[j].z + yv[j].w * yv[j].w; }
;       ss = wave_sum(ss); const float r = rsqrtf(ss * (1.f / 2048.f) + EPS);
; #pragma unroll
;       for (int j = 0; j < 8; ++j) { const f32x4 a = *(const f32x4*)(A1 + (j * 64 + lane) * 4); xv[j] += a * (yv[j] * r); }
;     }
;     if (yin || xout != xin) {
; #pragma unroll
;       for (int j = 0; j < 8; ++j) __builtin_nontemporal_store(xv[j], (f32x4*)(xout + (size_t)row * 2048 + (j * 64 + lane) * 4));
.Lrn_pf_skip3:
	s_or_b64 exec, exec, s[12:13]
	v_add_u32_e32 v36, s79, v36
	v_lshlrev_b32_e32 v66, 16, v58
	v_and_b32_e32 v67, 0xffff0000, v58
	v_lshlrev_b32_e32 v68, 16, v59
	v_and_b32_e32 v69, 0xffff0000, v59
	v_mul_f32_e32 v37, v67, v67
	v_fmac_f32_e32 v37, v66, v66
	v_fmac_f32_e32 v37, v68, v68
	v_fmac_f32_e32 v37, v69, v69
	v_lshlrev_b32_e32 v70, 16, v106
	v_and_b32_e32 v71, 0xffff0000, v106
	v_lshlrev_b32_e32 v72, 16, v107
	v_and_b32_e32 v73, 0xffff0000, v107
	v_mul_f32_e32 v41, v71, v71
	v_fmac_f32_e32 v41, v70, v70
	v_fmac_f32_e32 v41, v72, v72
	v_fmac_f32_e32 v41, v73, v73
	v_add_f32_e32 v37, v37, v41
	v_lshlrev_b32_e32 v74, 16, v108
	v_and_b32_e32 v75, 0xffff0000, v108
	v_lshlrev_b32_e32 v76, 16, v109
	v_and_b32_e32 v77, 0xffff0000, v109
	v_mul_f32_e32 v41, v75, v75
	v_fmac_f32_e32 v41, v74, v74
	v_fmac_f32_e32 v41, v76, v76
	v_fmac_f32_e32 v41, v77, v77
	v_add_f32_e32 v37, v37, v41
	v_lshlrev_b32_e32 v60, 16, v84
	v_and_b32_e32 v79, 0xffff0000, v110
	v_lshlrev_b32_e32 v78, 16, v110
	v_lshlrev_b32_e32 v80, 16, v111
	v_and_b32_e32 v81, 0xffff0000, v111
	v_mul_f32_e32 v41, v79, v79
	v_and_b32_e32 v59, 0xffff0000, v62
	v_and_b32_e32 v58, 0xffff0000, v84
	v_fmac_f32_e32 v41, v78, v78
	v_lshlrev_b32_e32 v61, 16, v62
	v_lshlrev_b32_e32 v64, 16, v85
	v_and_b32_e32 v62, 0xffff0000, v85
	v_pk_mul_f32 v[84:85], v[58:59], v[58:59]
	v_fmac_f32_e32 v41, v80, v80
	v_lshlrev_b32_e32 v65, 16, v63
	v_pk_fma_f32 v[84:85], v[60:61], v[60:61], v[84:85]
	v_fmac_f32_e32 v41, v81, v81
	v_and_b32_e32 v63, 0xffff0000, v63
	v_pk_fma_f32 v[84:85], v[64:65], v[64:65], v[84:85]
	v_add_f32_e32 v37, v37, v41
	v_pk_fma_f32 v[84:85], v[62:63], v[62:63], v[84:85]
	v_lshlrev_b32_e32 v83, 16, v88
	v_add_f32_e32 v37, v37, v84
	v_add_f32_e32 v37, v37, v85
	v_and_b32_e32 v85, 0xffff0000, v88
	v_and_b32_e32 v84, 0xffff0000, v98
	v_lshlrev_b32_e32 v82, 16, v98
	v_lshlrev_b32_e32 v86, 16, v99
	v_and_b32_e32 v88, 0xffff0000, v99
	v_pk_mul_f32 v[98:99], v[84:85], v[84:85]
	v_lshlrev_b32_e32 v87, 16, v89
	v_pk_fma_f32 v[98:99], v[82:83], v[82:83], v[98:99]
	v_and_b32_e32 v89, 0xffff0000, v89
	v_pk_fma_f32 v[98:99], v[86:87], v[86:87], v[98:99]
	s_nop 0
	v_pk_fma_f32 v[98:99], v[88:89], v[88:89], v[98:99]
	s_nop 0
	v_add_f32_e32 v37, v37, v98
	v_add_f32_e32 v37, v37, v99
	v_mov_b32_e32 v120, v37
	v_mov_b32_e32 v121, v37
	s_nop 1
	v_permlane32_swap_b32_e32 v120, v121
	ds_read_b128 v[98:101], v91
	s_waitcnt lgkmcnt(0)
	v_add_f32_e32 v37, v120, v121
	v_mov_b32_e32 v120, v37
	v_mov_b32_e32 v121, v37
	s_nop 1
	v_permlane16_swap_b32_e32 v120, v121
	s_waitcnt lgkmcnt(0)
	v_add_f32_e32 v37, v120, v121
	s_nop 1
	s_waitcnt lgkmcnt(0)
	v_add_f32_dpp v37, v37, v37 row_ror:8 row_mask:0xf bank_mask:0xf
	s_nop 1
	v_mov_b32_dpp v120, v37 row_ror:4 row_mask:0xf bank_mask:0xa
	v_mov_b32_dpp v120, v37 row_ror:12 row_mask:0xf bank_mask:0x5
	s_waitcnt lgkmcnt(0)
	v_add_f32_e32 v37, v37, v120
	s_nop 1
	s_waitcnt lgkmcnt(0)
	v_add_f32_dpp v37, v37, v37 quad_perm:[2,3,0,1] row_mask:0xf bank_mask:0xf
	s_nop 1
	s_waitcnt lgkmcnt(0)
	v_add_f32_dpp v37, v37, v37 quad_perm:[1,0,3,2] row_mask:0xf bank_mask:0xf
	v_fmamk_f32 v37, v37, 0x3a000000, v245
	v_cmp_gt_f32_e32 vcc, s84, v37
	v_mul_f32_e32 v41, 0x4b800000, v37
	s_nop 0
	v_cndmask_b32_e32 v37, v37, v41, vcc
	v_rsq_f32_e32 v37, v37
	s_nop 0
	v_mul_f32_e32 v41, 0x45800000, v37
	v_cndmask_b32_e32 v90, v37, v41, vcc
	v_pk_mul_f32 v[66:67], v[66:67], v[90:91] op_sel_hi:[1,0]
	v_pk_mul_f32 v[68:69], v[68:69], v[90:91] op_sel_hi:[1,0]
	v_pk_fma_f32 v[30:31], v[98:99], v[66:67], v[30:31]
	v_pk_fma_f32 v[32:33], v[100:101], v[68:69], v[32:33]
	ds_read_b128 v[66:69], v91 offset:1024
	v_pk_mul_f32 v[70:71], v[70:71], v[90:91] op_sel_hi:[1,0]
	v_pk_mul_f32 v[72:73], v[72:73], v[90:91] op_sel_hi:[1,0]
	v_cmp_lt_i32_e32 vcc, s4, v36
	s_or_b64 s[2:3], vcc, s[2:3]
	s_waitcnt lgkmcnt(0)
	v_pk_fma_f32 v[28:29], v[68:69], v[72:73], v[28:29]
	v_pk_fma_f32 v[26:27], v[66:67], v[70:71], v[26:27]
	ds_read_b128 v[66:69], v91 offset:2048
	v_pk_mul_f32 v[70:71], v[74:75], v[90:91] op_sel_hi:[1,0]
	v_pk_mul_f32 v[72:73], v[76:77], v[90:91] op_sel_hi:[1,0]
	s_waitcnt lgkmcnt(0)
	v_pk_fma_f32 v[22:23], v[66:67], v[70:71], v[22:23]
	v_pk_fma_f32 v[24:25], v[68:69], v[72:73], v[24:25]
	ds_read_b128 v[66:69], v91 offset:3072
	v_pk_mul_f32 v[70:71], v[78:79], v[90:91] op_sel_hi:[1,0]
	v_pk_mul_f32 v[72:73], v[80:81], v[90:91] op_sel_hi:[1,0]
	s_waitcnt lgkmcnt(0)
	v_pk_fma_f32 v[18:19], v[66:67], v[70:71], v[18:19]
	v_pk_fma_f32 v[20:21], v[68:69], v[72:73], v[20:21]
	ds_read_b128 v[66:69], v91 offset:4096
	v_mov_b32_e32 v70, v60
	v_mov_b32_e32 v71, v58
	v_mov_b32_e32 v72, v64
	v_mov_b32_e32 v73, v62
	v_pk_mul_f32 v[70:71], v[70:71], v[90:91] op_sel_hi:[1,0]
	v_pk_mul_f32 v[72:73], v[72:73], v[90:91] op_sel_hi:[1,0]
	s_waitcnt lgkmcnt(0)
	v_pk_fma_f32 v[14:15], v[66:67], v[70:71], v[14:15]
	v_pk_fma_f32 v[16:17], v[68:69], v[72:73], v[16:17]
	ds_read_b128 v[66:69], v91 offset:5120
	v_mov_b32_e32 v58, v61
	v_mov_b32_e32 v62, v65
	v_pk_mul_f32 v[58:59], v[58:59], v[90:91] op_sel_hi:[1,0]
	v_pk_mul_f32 v[60:61], v[62:63], v[90:91] op_sel_hi:[1,0]
	s_waitcnt lgkmcnt(0)
	v_pk_fma_f32 v[10:11], v[66:67], v[58:59], v[10:11]
	v_pk_fma_f32 v[12:13], v[68:69], v[60:61], v[12:13]
	ds_read_b128 v[58:61], v91 offset:6144
	v_mov_b32_e32 v62, v82
	v_mov_b32_e32 v63, v84
	v_mov_b32_e32 v64, v86
	v_mov_b32_e32 v65, v88
	v_pk_mul_f32 v[62:63], v[62:63], v[90:91] op_sel_hi:[1,0]
	v_pk_mul_f32 v[64:65], v[64:65], v[90:91] op_sel_hi:[1,0]
	s_waitcnt lgkmcnt(0)
	v_pk_fma_f32 v[6:7], v[58:59], v[62:63], v[6:7]
	v_pk_fma_f32 v[8:9], v[60:61], v[64:65], v[8:9]
	ds_read_b128 v[58:61], v91 offset:7168
	v_mov_b32_e32 v84, v83
	v_mov_b32_e32 v88, v87
	v_pk_mul_f32 v[62:63], v[84:85], v[90:91] op_sel_hi:[1,0]
	v_pk_mul_f32 v[64:65], v[88:89], v[90:91] op_sel_hi:[1,0]
	s_waitcnt lgkmcnt(0)
	v_pk_fma_f32 v[2:3], v[58:59], v[62:63], v[2:3]
	v_pk_fma_f32 v[4:5], v[60:61], v[64:65], v[4:5]
	global_store_dwordx4 v[54:55], v[30:33], off nt
	global_store_dwordx4 v[54:55], v[26:29], off offset:1024 nt
	global_store_dwordx4 v[54:55], v[22:25], off offset:2048 nt
	global_store_dwordx4 v[54:55], v[18:21], off offset:3072 nt
	global_store_dwordx4 v[56:57], v[14:17], off nt
	global_store_dwordx4 v[50:51], v[10:13], off nt
	global_store_dwordx4 v[48:49], v[6:9], off nt
	global_store_dwordx4 v[52:53], v[2:5], off nt
	s_andn2_b64 exec, exec, s[2:3]
	s_cbranch_execnz .LBB0_1157
